# v31 + barrier spin loops back off longer (s_sleep 4 instead of s_sleep 1)
# speedup vs baseline: 1.0010x; 1.0010x over previous
.Lmr_spin:
	global_load_dword v3, v0, s[10:11] sc1
	s_waitcnt vmcnt(0)
	v_cmp_gt_u32_e32 vcc, 0x30, v3
	s_cbranch_vccz .Lmr_ready
	s_sleep 4
	s_branch .Lmr_spin

.LBB0_184:
	v_readlane_b32 s4, v254, 5
	v_readlane_b32 s5, v254, 6
	v_readlane_b32 s6, v254, 2
	s_waitcnt lgkmcnt(0)
	s_nop 2
	global_load_dword v0, v129, s[4:5] sc1
	v_readlane_b32 s4, v254, 7
	v_readlane_b32 s5, v254, 8
	s_nop 4
	global_load_dword v1, v129, s[4:5] sc1
	v_readlane_b32 s4, v254, 9
	v_readlane_b32 s5, v254, 10
	s_waitcnt vmcnt(0)
	v_add_u32_e32 v16, v1, v0
	s_nop 2
	global_load_dword v2, v129, s[4:5] sc1
	v_readlane_b32 s4, v254, 11
	v_readlane_b32 s5, v254, 12
	s_waitcnt vmcnt(0)
	v_add_u32_e32 v16, v16, v2
	s_nop 2
	global_load_dword v3, v129, s[4:5] sc1
	v_readlane_b32 s4, v254, 13
	v_readlane_b32 s5, v254, 14
	s_waitcnt vmcnt(0)
	v_add_u32_e32 v16, v16, v3
	s_nop 2
	global_load_dword v4, v129, s[4:5] sc1
	v_readlane_b32 s4, v254, 15
	v_readlane_b32 s5, v254, 16
	s_waitcnt vmcnt(0)
	v_add_u32_e32 v16, v16, v4
	s_nop 2
	global_load_dword v5, v129, s[4:5] sc1
	v_readlane_b32 s4, v254, 17
	v_readlane_b32 s5, v254, 18
	s_waitcnt vmcnt(0)
	v_add_u32_e32 v16, v16, v5
	s_nop 2
	global_load_dword v6, v129, s[4:5] sc1
	v_readlane_b32 s4, v254, 19
	v_readlane_b32 s5, v254, 20
	s_waitcnt vmcnt(0)
	v_add_u32_e32 v16, v16, v6
	s_nop 2
	global_load_dword v7, v129, s[4:5] sc1
	v_readlane_b32 s4, v254, 21
	v_readlane_b32 s5, v254, 22
	s_waitcnt vmcnt(0)
	v_add_u32_e32 v16, v16, v7
	s_nop 2
	global_load_dword v8, v129, s[4:5] sc1
	v_readlane_b32 s4, v254, 23
	v_readlane_b32 s5, v254, 24
	s_waitcnt vmcnt(0)
	v_add_u32_e32 v16, v16, v8
	s_nop 2
	global_load_dword v9, v129, s[4:5] sc1
	v_readlane_b32 s4, v254, 25
	v_readlane_b32 s5, v254, 26
	s_waitcnt vmcnt(0)
	v_add_u32_e32 v16, v16, v9
	s_nop 2
	global_load_dword v10, v129, s[4:5] sc1
	v_readlane_b32 s4, v254, 27
	v_readlane_b32 s5, v254, 28
	s_waitcnt vmcnt(0)
	v_add_u32_e32 v16, v16, v10
	s_nop 2
	global_load_dword v11, v129, s[4:5] sc1
	v_readlane_b32 s4, v254, 29
	v_readlane_b32 s5, v254, 30
	s_waitcnt vmcnt(0)
	v_add_u32_e32 v16, v16, v11
	s_nop 2
	global_load_dword v12, v129, s[4:5] sc1
	v_readlane_b32 s4, v254, 31
	v_readlane_b32 s5, v254, 32
	s_waitcnt vmcnt(0)
	v_add_u32_e32 v16, v16, v12
	s_nop 2
	global_load_dword v13, v129, s[4:5] sc1
	v_readlane_b32 s4, v254, 33
	v_readlane_b32 s5, v254, 34
	s_waitcnt vmcnt(0)
	v_add_u32_e32 v16, v16, v13
	s_nop 2
	global_load_dword v14, v129, s[4:5] sc1
	v_readlane_b32 s4, v254, 35
	v_readlane_b32 s5, v254, 36
	s_waitcnt vmcnt(0)
	v_add_u32_e32 v16, v16, v14
	s_nop 2
	global_load_dword v15, v129, s[4:5] sc1
	s_mov_b64 s[4:5], -1
	s_waitcnt vmcnt(0)
	v_add_u32_e32 v16, v16, v15
	v_cmp_eq_u32_e32 vcc, s6, v16
	s_mov_b64 s[6:7], -1
	s_cbranch_vccnz .LBB0_183
	s_and_b32 s4, s11, 0xff
	s_cmp_eq_u32 s4, 0
	s_mov_b64 s[4:5], -1
	s_mov_b64 s[8:9], -1
	s_sleep 4
	s_cbranch_scc1 .LBB0_188
	s_and_b64 vcc, exec, s[8:9]
	s_cbranch_vccz .LBB0_183

.LBB0_202:
	s_and_b32 s18, s22, 0xff
	s_mov_b64 s[16:17], -1
	s_cmp_lg_u32 s18, 0
	s_mov_b64 s[20:21], -1
	s_sleep 4
	s_cbranch_scc0 .LBB0_205
	s_and_b64 vcc, exec, s[20:21]
	s_cbranch_vccz .LBB0_201

.LBB0_219:
	s_and_b32 s16, s20, 0xff
	s_mov_b64 s[14:15], -1
	s_cmp_lg_u32 s16, 0
	s_mov_b64 s[18:19], -1
	s_sleep 4
	s_cbranch_scc0 .LBB0_222
	s_and_b64 vcc, exec, s[18:19]
	s_cbranch_vccz .LBB0_218

.LBB0_1132:
	v_readlane_b32 s0, v254, 5
	v_readlane_b32 s1, v254, 6
	v_readlane_b32 s4, v254, 2
	s_waitcnt lgkmcnt(0)
	s_nop 2
	global_load_dword v0, v129, s[0:1] sc1
	v_readlane_b32 s0, v254, 7
	v_readlane_b32 s1, v254, 8
	s_nop 4
	global_load_dword v1, v129, s[0:1] sc1
	v_readlane_b32 s0, v254, 9
	v_readlane_b32 s1, v254, 10
	s_waitcnt vmcnt(0)
	v_add_u32_e32 v16, v1, v0
	s_nop 2
	global_load_dword v2, v129, s[0:1] sc1
	v_readlane_b32 s0, v254, 11
	v_readlane_b32 s1, v254, 12
	s_waitcnt vmcnt(0)
	v_add_u32_e32 v16, v16, v2
	s_nop 2
	global_load_dword v3, v129, s[0:1] sc1
	v_readlane_b32 s0, v254, 13
	v_readlane_b32 s1, v254, 14
	s_waitcnt vmcnt(0)
	v_add_u32_e32 v16, v16, v3
	s_nop 2
	global_load_dword v4, v129, s[0:1] sc1
	v_readlane_b32 s0, v254, 15
	v_readlane_b32 s1, v254, 16
	s_waitcnt vmcnt(0)
	v_add_u32_e32 v16, v16, v4
	s_nop 2
	global_load_dword v5, v129, s[0:1] sc1
	v_readlane_b32 s0, v254, 17
	v_readlane_b32 s1, v254, 18
	s_waitcnt vmcnt(0)
	v_add_u32_e32 v16, v16, v5
	s_nop 2
	global_load_dword v6, v129, s[0:1] sc1
	v_readlane_b32 s0, v254, 19
	v_readlane_b32 s1, v254, 20
	s_waitcnt vmcnt(0)
	v_add_u32_e32 v16, v16, v6
	s_nop 2
	global_load_dword v7, v129, s[0:1] sc1
	v_readlane_b32 s0, v254, 21
	v_readlane_b32 s1, v254, 22
	s_waitcnt vmcnt(0)
	v_add_u32_e32 v16, v16, v7
	s_nop 2
	global_load_dword v8, v129, s[0:1] sc1
	v_readlane_b32 s0, v254, 23
	v_readlane_b32 s1, v254, 24
	s_waitcnt vmcnt(0)
	v_add_u32_e32 v16, v16, v8
	s_nop 2
	global_load_dword v9, v129, s[0:1] sc1
	v_readlane_b32 s0, v254, 25
	v_readlane_b32 s1, v254, 26
	s_waitcnt vmcnt(0)
	v_add_u32_e32 v16, v16, v9
	s_nop 2
	global_load_dword v10, v129, s[0:1] sc1
	v_readlane_b32 s0, v254, 27
	v_readlane_b32 s1, v254, 28
	s_waitcnt vmcnt(0)
	v_add_u32_e32 v16, v16, v10
	s_nop 2
	global_load_dword v11, v129, s[0:1] sc1
	v_readlane_b32 s0, v254, 29
	v_readlane_b32 s1, v254, 30
	s_waitcnt vmcnt(0)
	v_add_u32_e32 v16, v16, v11
	s_nop 2
	global_load_dword v12, v129, s[0:1] sc1
	v_readlane_b32 s0, v254, 31
	v_readlane_b32 s1, v254, 32
	s_waitcnt vmcnt(0)
	v_add_u32_e32 v16, v16, v12
	s_nop 2
	global_load_dword v13, v129, s[0:1] sc1
	v_readlane_b32 s0, v254, 33
	v_readlane_b32 s1, v254, 34
	s_waitcnt vmcnt(0)
	v_add_u32_e32 v16, v16, v13
	s_nop 2
	global_load_dword v14, v129, s[0:1] sc1
	v_readlane_b32 s0, v254, 35
	v_readlane_b32 s1, v254, 36
	s_waitcnt vmcnt(0)
	v_add_u32_e32 v16, v16, v14
	s_nop 2
	global_load_dword v15, v129, s[0:1] sc1
	s_mov_b64 s[0:1], -1
	s_waitcnt vmcnt(0)
	v_add_u32_e32 v16, v16, v15
	v_cmp_eq_u32_e32 vcc, s4, v16
	s_mov_b64 s[4:5], -1
	s_cbranch_vccnz .LBB0_1131
	s_and_b32 s0, s9, 0xff
	s_cmp_eq_u32 s0, 0
	s_mov_b64 s[0:1], -1
	s_mov_b64 s[6:7], -1
	s_sleep 4
	s_cbranch_scc1 .LBB0_1136
	s_and_b64 vcc, exec, s[6:7]
	s_cbranch_vccz .LBB0_1131

.LBB0_1167:
	s_and_b32 s14, s18, 0xff
	s_mov_b64 s[12:13], -1
	s_cmp_lg_u32 s14, 0
	s_mov_b64 s[16:17], -1
	s_sleep 4
	s_cbranch_scc0 .LBB0_1170
	s_and_b64 vcc, exec, s[16:17]
	s_cbranch_vccz .LBB0_1166
